# ring7 plus: K/V fragment reads streamed one per MFMA, persistent packed softmax sums and LDS-DMA lane offsets
# baseline (speedup 1.0000x reference)
; template <int NS>
; DI void attn_item(const Params& p, int layer, char* smem, VBC& vc, int b, int hq, int qblk) {
;     ...
;     auto tile_ptrs = [&](int it, const u16*& kp, const u16*& vp) {
;         if (it < lat1 - lat0) { int kt = lat0 + it; kp = P + (size_t)(b * SEQ + kt * 64) * PC + kcol; vp = VT + kt * 64; }
;         else { int c = it - (lat1 - lat0); kp = P + (size_t)(NLAT + b * CTXL + c * 64) * PC + kcol; vp = VT + SEQ + c * 64; }
;     };
;     auto dma_tile = [&](int it, int st) {
;         const u16 *kp, *vp; tile_ptrs(it, kp, vp);
; #pragma unroll
;         for (int i = 0; i < 2; ++i) {
;             const int row = wave4 * 16 + i * 8 + drow;
;             const int chunk = dslot ^ ((row >> 1) & 7);
;             lds_u32* dk = (lds_u32*)(sK + st * 8192 + (wave4 * 16 + i * 8) * 64);
;             lds_u32* dv = (lds_u32*)(sK + st * 8192 + 4096 + (wave4 * 16 + i * 8) * 64);
;             __builtin_amdgcn_global_load_lds((const unsigned*)(kp + (size_t)row * PC + chunk * 8), dk, 16, 0, 0);
;             __builtin_amdgcn_global_load_lds((const unsigned*)(vp + (size_t)row * KVS + chunk * 8), dv, 16, 0, 0);
;         }
;     };
;     ...
;                 float mnew = fmaxf(mrun[m], tmax * cexp);
;                 if (fast) mnew = bf2f(f2bf(mnew));
;                 const float alpha = __builtin_amdgcn_exp2f(mrun[m] - mnew);
;                 mrun[m] = mnew;
;                 f32x2 ls2 = {0.f, 0.f};
;                 const f32x2 cc2 = {cexp, cexp}, mm2 = {-mnew, -mnew};
;     #pragma unroll
;                 for (int kt2 = 0; kt2 < 2; ++kt2)
;     #pragma unroll
;                     for (int e = 0; e < 16; e += 2) {
;                         f32x2 sv = {s[kt2][e], s[kt2][e + 1]};
;                         sv = __builtin_elementwise_fma(sv, cc2, mm2);
;                         f32x2 pv = {__builtin_amdgcn_exp2f(sv.x), __builtin_amdgcn_exp2f(sv.y)};
;                         s[kt2][e] = pv.x; s[kt2][e + 1] = pv.y; ls2 += pv;
;                     }
;                 lrun[m] = lrun[m] * alpha + (ls2.x + ls2.y);
;                 if (__any(alpha != 1.f)) {
;     #pragma unroll
;                     for (int t = 0; t < 2; ++t)
;     #pragma unroll
;                         for (int e = 0; e < 16; ++e) O[m][t][e] *= alpha;
;                 }
;                 if (fast) {
;                     qaug[m] = h == 0 ? (unsigned)f2bf(-mrun[m]) : 0u;
.Lr_takeover:
	v_readlane_b32 s0, v252, 21
	s_lshr_b32 s0, s0, 4
	s_add_i32 s0, s0, s33
	s_add_i32 s16, s0, 0x10000
	v_lshl_add_u32 v5, v241, 1, s33
	v_lshl_add_u32 v6, v243, 1, s33
	v_add_u32_e32 v12, v206, v222
	v_add_u32_e32 v13, v208, v222
	v_readfirstlane_b32 s98, v5
	v_readfirstlane_b32 s99, v6
	v_add_u32_e32 v193, v210, v224
	v_add_u32_e32 v195, v212, v224
	s_mov_b32 s47, 2
	s_mov_b32 s55, 0x8000
	s_cmp_lt_u32 s47, s21
	s_cselect_b64 s[0:1], -1, 0
	s_sub_i32 s17, s47, s21
	s_min_u32 s17, s47, s17
	s_and_b64 s[0:1], s[0:1], exec
	s_cselect_b32 s0, s20, s27
	s_cselect_b32 s1, s25, s41
	s_cselect_b32 s48, s24, s40
	s_lshl_b32 s49, s17, 6
	s_add_i32 s49, s49, s0
	s_lshl_b32 s0, s17, 7
	s_add_u32 s0, s48, s0
	s_addc_u32 s1, s1, 0
	s_mul_hi_i32 s17, s49, 0x1a80
	s_mulk_i32 s49, 0x1a80
	s_add_u32 s48, s42, s49
	s_addc_u32 s49, s43, s17
	s_add_i32 m0, s98, s55
	s_nop 0
	global_load_lds_dwordx4 v12, s[48:49]
	s_add_i32 m0, m0, 0x2000
	s_nop 0
	global_load_lds_dwordx4 v13, s[0:1]
	s_add_i32 m0, s99, s55
	s_nop 0
	global_load_lds_dwordx4 v193, s[48:49]
	s_add_i32 m0, m0, 0x2000
	s_nop 0
	global_load_lds_dwordx4 v195, s[0:1]
	s_mov_b32 s47, 3
	s_mov_b32 s55, 0xc000
	s_cmp_lt_u32 s47, s21
	s_cselect_b64 s[0:1], -1, 0
	s_sub_i32 s17, s47, s21
	s_min_u32 s17, s47, s17
	s_and_b64 s[0:1], s[0:1], exec
	s_cselect_b32 s0, s20, s27
	s_cselect_b32 s1, s25, s41
	s_cselect_b32 s48, s24, s40
	s_lshl_b32 s49, s17, 6
	s_add_i32 s49, s49, s0
	s_lshl_b32 s0, s17, 7
	s_add_u32 s0, s48, s0
	s_addc_u32 s1, s1, 0
	s_mul_hi_i32 s17, s49, 0x1a80
	s_mulk_i32 s49, 0x1a80
	s_add_u32 s48, s42, s49
	s_addc_u32 s49, s43, s17
	s_add_i32 m0, s98, s55
	s_nop 0
	global_load_lds_dwordx4 v12, s[48:49]
	s_add_i32 m0, m0, 0x2000
	s_nop 0
	global_load_lds_dwordx4 v13, s[0:1]
	s_add_i32 m0, s99, s55
	s_nop 0
	global_load_lds_dwordx4 v193, s[48:49]
	s_add_i32 m0, m0, 0x2000
	s_nop 0
	global_load_lds_dwordx4 v195, s[0:1]
	v_max_f32_e32 v226, v7, v249
	v_sub_f32_e32 v5, v7, v226
	v_sub_f32_e32 v6, v249, v226
	v_exp_f32_e32 v5, v5
	v_exp_f32_e32 v6, v6
	v_xor_b32_e32 v128, 0x80000000, v226
	v_xor_b32_e32 v129, 0x80000000, v226
	v_xor_b32_e32 v130, 0x80000000, v226
	v_xor_b32_e32 v131, 0x80000000, v226
	v_xor_b32_e32 v132, 0x80000000, v226
	v_xor_b32_e32 v133, 0x80000000, v226
	v_xor_b32_e32 v134, 0x80000000, v226
	v_xor_b32_e32 v135, 0x80000000, v226
	v_xor_b32_e32 v136, 0x80000000, v226
	v_xor_b32_e32 v137, 0x80000000, v226
	v_xor_b32_e32 v138, 0x80000000, v226
	v_xor_b32_e32 v139, 0x80000000, v226
	v_xor_b32_e32 v140, 0x80000000, v226
	v_xor_b32_e32 v141, 0x80000000, v226
	v_xor_b32_e32 v142, 0x80000000, v226
	v_xor_b32_e32 v143, 0x80000000, v226
	v_mul_f32_e32 v2, v194, v5
	v_mov_b32_e32 v3, 0
	v_mul_f32_e32 v14, v4, v6
	v_mov_b32_e32 v15, 0
	v_mul_f32_e32 v64, v64, v5
	v_mul_f32_e32 v65, v65, v5
	v_mul_f32_e32 v66, v66, v5
	v_mul_f32_e32 v67, v67, v5
	v_mul_f32_e32 v68, v68, v5
	v_mul_f32_e32 v69, v69, v5
	v_mul_f32_e32 v70, v70, v5
	v_mul_f32_e32 v71, v71, v5
	v_mul_f32_e32 v72, v72, v5
	v_mul_f32_e32 v73, v73, v5
	v_mul_f32_e32 v74, v74, v5
	v_mul_f32_e32 v75, v75, v5
	v_mul_f32_e32 v76, v76, v5
	v_mul_f32_e32 v77, v77, v5
	v_mul_f32_e32 v78, v78, v5
	v_mul_f32_e32 v79, v79, v5
	v_mul_f32_e32 v32, v32, v5
	v_mul_f32_e32 v33, v33, v5
	v_mul_f32_e32 v34, v34, v5
	v_mul_f32_e32 v35, v35, v5
	v_mul_f32_e32 v36, v36, v5
	v_mul_f32_e32 v37, v37, v5
	v_mul_f32_e32 v38, v38, v5
	v_mul_f32_e32 v39, v39, v5
	v_mul_f32_e32 v40, v40, v5
	v_mul_f32_e32 v41, v41, v5
	v_mul_f32_e32 v42, v42, v5
	v_mul_f32_e32 v43, v43, v5
	v_mul_f32_e32 v44, v44, v5
	v_mul_f32_e32 v45, v45, v5
	v_mul_f32_e32 v46, v46, v5
	v_mul_f32_e32 v47, v47, v5
	v_mul_f32_e32 v48, v48, v6
	v_mul_f32_e32 v49, v49, v6
	v_mul_f32_e32 v50, v50, v6
	v_mul_f32_e32 v51, v51, v6
	v_mul_f32_e32 v52, v52, v6
	v_mul_f32_e32 v53, v53, v6
	v_mul_f32_e32 v54, v54, v6
	v_mul_f32_e32 v55, v55, v6
	v_mul_f32_e32 v56, v56, v6
	v_mul_f32_e32 v57, v57, v6
	v_mul_f32_e32 v58, v58, v6
	v_mul_f32_e32 v59, v59, v6
	v_mul_f32_e32 v60, v60, v6
	v_mul_f32_e32 v61, v61, v6
	v_mul_f32_e32 v62, v62, v6
	v_mul_f32_e32 v63, v63, v6
	v_mul_f32_e32 v16, v16, v6
	v_mul_f32_e32 v17, v17, v6
	v_mul_f32_e32 v18, v18, v6
	v_mul_f32_e32 v19, v19, v6
	v_mul_f32_e32 v20, v20, v6
	v_mul_f32_e32 v21, v21, v6
	v_mul_f32_e32 v22, v22, v6
	v_mul_f32_e32 v23, v23, v6
	v_mul_f32_e32 v24, v24, v6
	v_mul_f32_e32 v25, v25, v6
	v_mul_f32_e32 v26, v26, v6
	v_mul_f32_e32 v27, v27, v6
	v_mul_f32_e32 v28, v28, v6
	v_mul_f32_e32 v29, v29, v6
	v_mul_f32_e32 v30, v30, v6
	v_mul_f32_e32 v31, v31, v6
	v_mov_b32_e32 v7, v226
	v_mov_b32_e32 v249, v226
	s_add_i32 s0, s33, 0x10000
	v_mov_b32_e32 v0, s0
	s_movk_i32 s17, 0x2000
; template <int NS>
; DI void attn_item(const Params& p, int layer, char* smem, VBC& vc, int b, int hq, int qblk) {
;     ...
;         auto qk = [&](const int m, f32x16 (&s)[2]) {
; #pragma unroll
;             for (int kt2 = 0; kt2 < 2; ++kt2)
; #pragma unroll
;                 for (int e = 0; e < 16; ++e) s[kt2][e] = 0.f;
;             __builtin_amdgcn_s_setprio(1);
; #pragma unroll
;             for (int ks = 0; ks < NKS; ++ks)
; #pragma unroll
;                 for (int kt2 = 0; kt2 < 2; ++kt2) s[kt2] = MFMA(ld8(cK + (kt2 * 32 + r) * 64 + (((m * DQK + ks * 16)) ^ hs16)), qf[m][ks], s[kt2]);
; #pragma unroll
;             for (int kt2 = 0; kt2 < 2; ++kt2) { uint4 qa4 = {qaug[m], 0u, 0u, 0u}; s[kt2] = MFMA(kones, __builtin_bit_cast(bf16x8, qa4), s[kt2]); }
;             __builtin_amdgcn_s_setprio(0);
;     ...
;             if (fixed) {
;                 float ls = 0.f;
; #pragma unroll
;                 for (int kt2 = 0; kt2 < 2; ++kt2)
; #pragma unroll
;                     for (int e = 0; e < 16; ++e) { const float pv = __builtin_amdgcn_exp2f(s[kt2][e]); s[kt2][e] = pv; ls += pv; }
;                 lrun[m] += ls;
;             } else {
;                 float tmax = -1e30f;
;     #pragma unroll
;                 for (int kt2 = 0; kt2 < 2; ++kt2)
;     #pragma unroll
;                     for (int e = 0; e < 16; ++e) tmax = fmaxf(tmax, s[kt2][e]);
;                 tmax = fmaxf(tmax, __shfl_xor(tmax, 32));
;                 float mnew = fmaxf(mrun[m], tmax * cexp);
;                 if (fast) mnew = bf2f(f2bf(mnew));
;                 const float alpha = __builtin_amdgcn_exp2f(mrun[m] - mnew);
;                 mrun[m] = mnew;
;                 f32x2 ls2 = {0.f, 0.f};
;                 const f32x2 cc2 = {cexp, cexp}, mm2 = {-mnew, -mnew};
;     #pragma unroll
;                 for (int kt2 = 0; kt2 < 2; ++kt2)
;     #pragma unroll
;                     for (int e = 0; e < 16; e += 2) {
;                         f32x2 sv = {s[kt2][e], s[kt2][e + 1]};
;                         sv = __builtin_elementwise_fma(sv, cc2, mm2);
;                         f32x2 pv = {__builtin_amdgcn_exp2f(sv.x), __builtin_amdgcn_exp2f(sv.y)};
;                         s[kt2][e] = pv.x; s[kt2][e + 1] = pv.y; ls2 += pv;
;                     }
;                 lrun[m] = lrun[m] * alpha + (ls2.x + ls2.y);
;                 if (__any(alpha != 1.f)) {
;     #pragma unroll
.Lr_body:
	v_lshl_add_u32 v226, s17, 1, v248
	v_lshl_add_u32 v5, v201, 1, v226
	v_lshl_add_u32 v6, v245, 1, v226
	ds_read_b128 v[112:115], v5
	ds_read_b128 v[116:119], v5 offset:4096
	ds_read_b128 v[120:123], v6
	ds_read_b128 v[124:127], v6 offset:4096
	v_lshl_add_u32 v223, v246, 1, v226
	v_lshl_add_u32 v225, v247, 1, v226
	s_waitcnt lgkmcnt(3)
	v_mfma_f32_32x32x16_bf16 v[96:111], v[112:115], v[176:179], v[128:143]
	ds_read_b128 v[112:115], v223
	s_waitcnt lgkmcnt(3)
	v_mfma_f32_32x32x16_bf16 v[80:95], v[116:119], v[176:179], v[128:143]
	ds_read_b128 v[116:119], v223 offset:4096
	s_waitcnt lgkmcnt(3)
	v_mfma_f32_32x32x16_bf16 v[96:111], v[120:123], v[180:183], v[96:111]
	ds_read_b128 v[120:123], v225
	s_waitcnt lgkmcnt(3)
	v_mfma_f32_32x32x16_bf16 v[80:95], v[124:127], v[180:183], v[80:95]
	ds_read_b128 v[124:127], v225 offset:4096
	s_waitcnt lgkmcnt(3)
	v_mfma_f32_32x32x16_bf16 v[144:159], v[112:115], v[184:187], v[128:143]
	ds_read_b128 v[112:115], v5 offset:8192
	s_waitcnt lgkmcnt(3)
	v_mfma_f32_32x32x16_bf16 v[160:175], v[116:119], v[184:187], v[128:143]
	ds_read_b128 v[116:119], v5 offset:12288
	s_waitcnt lgkmcnt(3)
	v_mfma_f32_32x32x16_bf16 v[144:159], v[120:123], v[188:191], v[144:159]
	ds_read_b128 v[120:123], v6 offset:8192
	s_waitcnt lgkmcnt(3)
	v_mfma_f32_32x32x16_bf16 v[160:175], v[124:127], v[188:191], v[160:175]
	ds_read_b128 v[124:127], v6 offset:12288
	v_exp_f32_e32 v96, v96
	v_exp_f32_e32 v97, v97
	v_exp_f32_e32 v98, v98
	v_exp_f32_e32 v99, v99
	v_pk_add_f32 v[2:3], v[2:3], v[96:97]
	v_exp_f32_e32 v100, v100
	v_exp_f32_e32 v101, v101
	v_pk_add_f32 v[2:3], v[2:3], v[98:99]
	v_exp_f32_e32 v102, v102
	v_exp_f32_e32 v103, v103
	v_pk_add_f32 v[2:3], v[2:3], v[100:101]
	v_exp_f32_e32 v104, v104
	v_exp_f32_e32 v105, v105
	v_pk_add_f32 v[2:3], v[2:3], v[102:103]
	v_exp_f32_e32 v106, v106
	v_exp_f32_e32 v107, v107
	v_pk_add_f32 v[2:3], v[2:3], v[104:105]
	v_exp_f32_e32 v108, v108
	v_exp_f32_e32 v109, v109
	v_pk_add_f32 v[2:3], v[2:3], v[106:107]
	v_exp_f32_e32 v110, v110
	v_exp_f32_e32 v111, v111
	v_pk_add_f32 v[2:3], v[2:3], v[108:109]
	v_exp_f32_e32 v80, v80
	v_exp_f32_e32 v81, v81
	v_pk_add_f32 v[2:3], v[2:3], v[110:111]
	v_exp_f32_e32 v82, v82
	v_exp_f32_e32 v83, v83
	v_pk_add_f32 v[2:3], v[2:3], v[80:81]
	v_exp_f32_e32 v84, v84
	v_exp_f32_e32 v85, v85
	v_pk_add_f32 v[2:3], v[2:3], v[82:83]
	v_exp_f32_e32 v86, v86
	v_exp_f32_e32 v87, v87
	v_pk_add_f32 v[2:3], v[2:3], v[84:85]
	v_exp_f32_e32 v88, v88
	v_exp_f32_e32 v89, v89
	v_pk_add_f32 v[2:3], v[2:3], v[86:87]
	v_exp_f32_e32 v90, v90
	v_exp_f32_e32 v91, v91
	v_pk_add_f32 v[2:3], v[2:3], v[88:89]
	v_exp_f32_e32 v92, v92
	v_exp_f32_e32 v93, v93
	v_pk_add_f32 v[2:3], v[2:3], v[90:91]
	v_exp_f32_e32 v94, v94
	v_exp_f32_e32 v95, v95
	v_pk_add_f32 v[2:3], v[2:3], v[92:93]
	s_nop 0
	v_pk_add_f32 v[2:3], v[2:3], v[94:95]
	v_cvt_pk_bf16_f32 v96, v96, v97
	v_cvt_pk_bf16_f32 v97, v98, v99
	v_cvt_pk_bf16_f32 v98, v100, v101
	v_cvt_pk_bf16_f32 v99, v102, v103
	v_cvt_pk_bf16_f32 v100, v104, v105
	v_cvt_pk_bf16_f32 v101, v106, v107
	v_cvt_pk_bf16_f32 v102, v108, v109
	v_cvt_pk_bf16_f32 v103, v110, v111
	v_cvt_pk_bf16_f32 v80, v80, v81
	v_cvt_pk_bf16_f32 v81, v82, v83
	v_cvt_pk_bf16_f32 v82, v84, v85
	v_cvt_pk_bf16_f32 v83, v86, v87
	v_cvt_pk_bf16_f32 v84, v88, v89
	v_cvt_pk_bf16_f32 v85, v90, v91
	v_cvt_pk_bf16_f32 v86, v92, v93
	v_cvt_pk_bf16_f32 v87, v94, v95
	ds_read_b128 v[104:107], v223 offset:8192
	ds_read_b128 v[108:111], v223 offset:12288
	ds_read_b128 v[88:91], v225 offset:8192
	ds_read_b128 v[92:95], v225 offset:12288
	s_waitcnt lgkmcnt(7)
	v_mfma_f32_32x32x16_bf16 v[64:79], v[112:115], v[96:99], v[64:79]
	v_exp_f32_e32 v144, v144
	v_exp_f32_e32 v145, v145
	v_exp_f32_e32 v146, v146
	v_exp_f32_e32 v147, v147
	v_pk_add_f32 v[14:15], v[14:15], v[144:145]
	v_exp_f32_e32 v148, v148
	v_exp_f32_e32 v149, v149
	v_pk_add_f32 v[14:15], v[14:15], v[146:147]
	s_waitcnt lgkmcnt(6)
	v_mfma_f32_32x32x16_bf16 v[32:47], v[116:119], v[96:99], v[32:47]
	v_exp_f32_e32 v150, v150
	v_exp_f32_e32 v151, v151
	v_pk_add_f32 v[14:15], v[14:15], v[148:149]
	v_exp_f32_e32 v152, v152
	v_exp_f32_e32 v153, v153
	v_pk_add_f32 v[14:15], v[14:15], v[150:151]
	v_exp_f32_e32 v154, v154
	v_exp_f32_e32 v155, v155
	s_waitcnt lgkmcnt(5)
	v_mfma_f32_32x32x16_bf16 v[64:79], v[120:123], v[100:103], v[64:79]
	v_pk_add_f32 v[14:15], v[14:15], v[152:153]
	v_exp_f32_e32 v156, v156
	v_exp_f32_e32 v157, v157
	v_pk_add_f32 v[14:15], v[14:15], v[154:155]
	v_exp_f32_e32 v158, v158
	v_exp_f32_e32 v159, v159
	v_pk_add_f32 v[14:15], v[14:15], v[156:157]
	v_exp_f32_e32 v160, v160
	s_waitcnt lgkmcnt(4)
	v_mfma_f32_32x32x16_bf16 v[32:47], v[124:127], v[100:103], v[32:47]
	v_exp_f32_e32 v161, v161
	v_pk_add_f32 v[14:15], v[14:15], v[158:159]
	v_exp_f32_e32 v162, v162
	v_exp_f32_e32 v163, v163
	v_pk_add_f32 v[14:15], v[14:15], v[160:161]
	v_exp_f32_e32 v164, v164
	v_exp_f32_e32 v165, v165
	v_pk_add_f32 v[14:15], v[14:15], v[162:163]
	s_waitcnt lgkmcnt(3)
	v_mfma_f32_32x32x16_bf16 v[64:79], v[104:107], v[80:83], v[64:79]
	v_exp_f32_e32 v166, v166
	v_exp_f32_e32 v167, v167
	v_pk_add_f32 v[14:15], v[14:15], v[164:165]
	v_exp_f32_e32 v168, v168
	v_exp_f32_e32 v169, v169
	v_pk_add_f32 v[14:15], v[14:15], v[166:167]
	v_exp_f32_e32 v170, v170
	v_exp_f32_e32 v171, v171
	s_waitcnt lgkmcnt(2)
	v_mfma_f32_32x32x16_bf16 v[32:47], v[108:111], v[80:83], v[32:47]
	v_pk_add_f32 v[14:15], v[14:15], v[168:169]
	v_exp_f32_e32 v172, v172
	v_exp_f32_e32 v173, v173
	v_pk_add_f32 v[14:15], v[14:15], v[170:171]
	v_exp_f32_e32 v174, v174
	v_exp_f32_e32 v175, v175
	v_pk_add_f32 v[14:15], v[14:15], v[172:173]
	s_nop 0
	s_waitcnt lgkmcnt(1)
	v_mfma_f32_32x32x16_bf16 v[64:79], v[88:91], v[84:87], v[64:79]
	v_pk_add_f32 v[14:15], v[14:15], v[174:175]
	s_waitcnt lgkmcnt(0)
	v_mfma_f32_32x32x16_bf16 v[32:47], v[92:95], v[84:87], v[32:47]
	v_cvt_pk_bf16_f32 v144, v144, v145
	v_cvt_pk_bf16_f32 v145, v146, v147
	v_cvt_pk_bf16_f32 v146, v148, v149
	v_cvt_pk_bf16_f32 v147, v150, v151
	v_cvt_pk_bf16_f32 v148, v152, v153
	v_cvt_pk_bf16_f32 v149, v154, v155
	v_cvt_pk_bf16_f32 v150, v156, v157
	v_cvt_pk_bf16_f32 v151, v158, v159
	v_cvt_pk_bf16_f32 v160, v160, v161
	v_cvt_pk_bf16_f32 v161, v162, v163
	v_cvt_pk_bf16_f32 v162, v164, v165
	v_cvt_pk_bf16_f32 v163, v166, v167
	v_cvt_pk_bf16_f32 v164, v168, v169
	v_cvt_pk_bf16_f32 v165, v170, v171
	v_cvt_pk_bf16_f32 v166, v172, v173
	v_cvt_pk_bf16_f32 v167, v174, v175
	s_nop 1
	s_cmp_lg_u32 s46, s44
	s_cbranch_scc0 .Lr_last
; #define MFMA(a, b, c) __builtin_amdgcn_mfma_f32_32x32x16_bf16((a), (b), (c), 0, 0, 0)
; #define VSYNC() vb_sync(vc)
; template <int NS>
; DI void attn_item(const Params& p, int layer, char* smem, VBC& vc, int b, int hq, int qblk) {
;     ...
;     auto tile_ptrs = [&](int it, const u16*& kp, const u16*& vp) {
;         if (it < lat1 - lat0) { int kt = lat0 + it; kp = P + (size_t)(b * SEQ + kt * 64) * PC + kcol; vp = VT + kt * 64; }
;         else { int c = it - (lat1 - lat0); kp = P + (size_t)(NLAT + b * CTXL + c * 64) * PC + kcol; vp = VT + SEQ + c * 64; }
;     };
;     auto dma_tile = [&](int it, int st) {
;         const u16 *kp, *vp; tile_ptrs(it, kp, vp);
; #pragma unroll
;         for (int i = 0; i < 2; ++i) {
;             const int row = wave4 * 16 + i * 8 + drow;
;             const int chunk = dslot ^ ((row >> 1) & 7);
;             lds_u32* dk = (lds_u32*)(sK + st * 8192 + (wave4 * 16 + i * 8) * 64);
;             lds_u32* dv = (lds_u32*)(sK + st * 8192 + 4096 + (wave4 * 16 + i * 8) * 64);
;             __builtin_amdgcn_global_load_lds((const unsigned*)(kp + (size_t)row * PC + chunk * 8), dk, 16, 0, 0);
;             __builtin_amdgcn_global_load_lds((const unsigned*)(vp + (size_t)row * KVS + chunk * 8), dv, 16, 0, 0);
;         }
;     };
;     const int hs16 = ((h ^ ((r >> 1) & 7)) << 3);
;     const bf16x8 kones = __builtin_bit_cast(bf16x8, (uint4){0x00003F80u, 0u, 0u, 0u});
;     auto run_tiles = [&](const bool fast) {
;     dma_tile(0, 0);
;     asm volatile("s_waitcnt vmcnt(0)" ::: "memory");
;     VSYNC();
;     for (int it = 0; it < ntiles; ++it) {
;         const int buf = it & 1;
;         if (it + 1 < ntiles) dma_tile(it + 1, buf ^ 1);
;     ...
;         auto pvm = [&](const int m, const bf16x8 (&pf)[2][2]) {
;             __builtin_amdgcn_s_setprio(1);
; #pragma unroll
;             for (int kk = 0; kk < 4; ++kk)
; #pragma unroll
;                 for (int dvt = 0; dvt < 2; ++dvt) O[m][dvt] = MFMA(ld8(cV + (dvt * 32 + r) * 64 + ((kk * 16) ^ hs16)), pf[kk >> 1][kk & 1], O[m][dvt]);
;             __builtin_amdgcn_s_setprio(0);
;         };
	v_mfma_f32_32x32x16_bf16 v[48:63], v[112:115], v[144:147], v[48:63]
	s_waitcnt vmcnt(0)
	v_mov_b32_e32 v5, s16
	v_mov_b32_e32 v6, s46
	s_mov_b64 exec, 1
	ds_write_b32 v5, v6
	s_mov_b64 exec, -1
	ds_read_b128 v[8:11], v0
	v_mfma_f32_32x32x16_bf16 v[16:31], v[116:119], v[144:147], v[16:31]
	s_add_i32 s54, s46, -1
	s_max_i32 s54, s54, 1
	s_add_i32 s47, s46, 3
	s_and_b32 s55, s47, 3
	s_lshl_b32 s55, s55, 14
	s_cmp_lt_u32 s47, s21
	s_cselect_b64 s[0:1], -1, 0
	s_sub_i32 s17, s47, s21
	s_min_u32 s17, s47, s17
	s_and_b64 s[0:1], s[0:1], exec
	s_cselect_b32 s0, s20, s27
	s_cselect_b32 s1, s25, s41
	s_cselect_b32 s48, s24, s40
	s_lshl_b32 s49, s17, 6
	s_add_i32 s49, s49, s0
	s_lshl_b32 s0, s17, 7
	s_add_u32 s0, s48, s0
	s_addc_u32 s1, s1, 0
	s_mul_hi_i32 s17, s49, 0x1a80
	s_mulk_i32 s49, 0x1a80
	s_add_u32 s48, s42, s49
	s_addc_u32 s49, s43, s17
	v_mfma_f32_32x32x16_bf16 v[48:63], v[120:123], v[148:151], v[48:63]
	s_waitcnt lgkmcnt(0)
	v_min3_u32 v8, v8, v9, v10
	v_min_u32_e32 v8, v8, v11
	v_mfma_f32_32x32x16_bf16 v[16:31], v[124:127], v[148:151], v[16:31]
	v_cmp_gt_u32_e32 vcc, s54, v8
	s_cbranch_vccnz .Lr_pollslow
.Lr_ready:
	s_cmp_lt_u32 s47, s26
	s_cbranch_scc0 .Lr_nodma
	s_add_i32 m0, s98, s55
	s_nop 0
	global_load_lds_dwordx4 v12, s[48:49]
	v_mfma_f32_32x32x16_bf16 v[48:63], v[104:107], v[160:163], v[48:63]
	s_add_i32 m0, m0, 0x2000
	s_nop 0
	global_load_lds_dwordx4 v13, s[0:1]
	v_mfma_f32_32x32x16_bf16 v[16:31], v[108:111], v[160:163], v[16:31]
	s_add_i32 m0, s99, s55
	s_nop 0
	global_load_lds_dwordx4 v193, s[48:49]
	v_mfma_f32_32x32x16_bf16 v[48:63], v[88:91], v[164:167], v[48:63]
	s_add_i32 m0, m0, 0x2000
	s_nop 0
	global_load_lds_dwordx4 v195, s[0:1]
	v_mfma_f32_32x32x16_bf16 v[16:31], v[92:95], v[164:167], v[16:31]
	s_branch .Lr_next

; #define MFMA(a, b, c) __builtin_amdgcn_mfma_f32_32x32x16_bf16((a), (b), (c), 0, 0, 0)
; template <int NS>
; DI void attn_item(const Params& p, int layer, char* smem, VBC& vc, int b, int hq, int qblk) {
;     ...
;         auto pvm = [&](const int m, const bf16x8 (&pf)[2][2]) {
;             __builtin_amdgcn_s_setprio(1);
; #pragma unroll
;             for (int kk = 0; kk < 4; ++kk)
; #pragma unroll
;                 for (int dvt = 0; dvt < 2; ++dvt) O[m][dvt] = MFMA(ld8(cV + (dvt * 32 + r) * 64 + ((kk * 16) ^ hs16)), pf[kk >> 1][kk & 1], O[m][dvt]);
;             __builtin_amdgcn_s_setprio(0);
;         };
;     ...
;     for (int attempt = 0; attempt < 2; ++attempt) {
;         if (attempt) init_state();
;         run_tiles(attempt == 0);
;         bool bad = !(lrun[0] < 1e37f);
;         if (NS == 2) bad = bad || !(lrun[NS - 1] < 1e37f);
.Lr_pollslow:
	s_sleep 1
	ds_read_b128 v[8:11], v0
	s_waitcnt lgkmcnt(0)
	v_min3_u32 v8, v8, v9, v10
	v_min_u32_e32 v8, v8, v11
	v_cmp_gt_u32_e32 vcc, s54, v8
	s_cbranch_vccnz .Lr_pollslow
	s_branch .Lr_ready
.Lr_last:
	v_mfma_f32_32x32x16_bf16 v[48:63], v[112:115], v[144:147], v[48:63]
	v_mfma_f32_32x32x16_bf16 v[16:31], v[116:119], v[144:147], v[16:31]
	v_mfma_f32_32x32x16_bf16 v[48:63], v[120:123], v[148:151], v[48:63]
	v_mfma_f32_32x32x16_bf16 v[16:31], v[124:127], v[148:151], v[16:31]
	v_mfma_f32_32x32x16_bf16 v[48:63], v[104:107], v[160:163], v[48:63]
	v_mfma_f32_32x32x16_bf16 v[16:31], v[108:111], v[160:163], v[16:31]
	v_mfma_f32_32x32x16_bf16 v[48:63], v[88:91], v[164:167], v[48:63]
	v_mfma_f32_32x32x16_bf16 v[16:31], v[92:95], v[164:167], v[16:31]
	v_add_f32_e32 v194, v2, v3
	v_add_f32_e32 v4, v14, v15
	s_mov_b32 s0, 0x0da24260
	v_mov_b32_e32 v2, 0x7f800000
	v_cmp_gt_f32_e32 vcc, s0, v194
	s_nop 1
	v_cndmask_b32_e32 v223, v194, v2, vcc
	v_cmp_gt_f32_e32 vcc, s0, v4
	s_nop 1
	v_cndmask_b32_e32 v193, v4, v2, vcc
	v_mov_b32_e32 v226, v7
	v_mov_b32_e32 v3, v1
	v_mov_b32_e32 v0, v249
	v_mov_b32_e32 v195, v192
	s_waitcnt vmcnt(0)
	s_add_i32 s45, s45, -4
	s_branch .LBB0_964
